# summary tile loop: MFMAs read next-tile weights straight from their landing registers, prefetch split in two halves after the last reader, 22 rotation moves per tile removed; packed x+0 adds folded
# speedup vs baseline: 1.0032x; 1.0032x over previous
.LBB0_425:
	s_or_b64 exec, exec, s[34:35]
	s_waitcnt lgkmcnt(0)
	v_pk_add_f32 v[16:17], v[98:99], v[110:111]
	v_pk_add_f32 v[98:99], v[100:101], v[0:1]
	s_add_i32 s39, s39, 16
	v_pk_add_f32 v[2:3], v[102:103], v[2:3]
	v_cvt_pk_bf16_f32 v2, v2, v3
	v_pk_add_f32 v[4:5], v[106:107], v[4:5]
	v_cvt_pk_bf16_f32 v3, v4, v5
	v_pk_add_f32 v[6:7], v[108:109], v[6:7]
	v_lshl_add_u64 v[4:5], v[112:113], 0, s[18:19]
	v_pk_add_f32 v[10:11], v[92:93], v[10:11]
	s_add_u32 s30, s30, 0x800
	v_pk_add_f32 v[14:15], v[94:95], v[14:15]
	v_pk_add_f32 v[12:13], v[88:89], v[12:13]
	v_mov_b32_e32 v88, v89
	v_cvt_pk_bf16_f32 v0, v16, v17
	v_cvt_pk_bf16_f32 v1, v98, v99
	global_store_dwordx4 v[112:113], v[0:3], off sc1
	s_nop 1
	v_cvt_pk_bf16_f32 v0, v6, v7
	v_cvt_pk_bf16_f32 v1, v10, v11
	v_cvt_pk_bf16_f32 v2, v14, v15
	v_cvt_pk_bf16_f32 v3, v12, v13
	global_store_dwordx4 v[4:5], v[0:3], off sc1
	s_nop 1
	v_cvt_pk_bf16_f32 v0, v96, v97
	v_cvt_pk_bf16_f32 v1, v203, v204
	v_cvt_pk_bf16_f32 v2, v205, v207
	v_cvt_pk_bf16_f32 v3, v208, v212
	v_lshl_add_u64 v[4:5], v[112:113], 0, s[12:13]
	global_store_dwordx4 v[4:5], v[0:3], off sc1
	s_nop 1
	v_cvt_pk_bf16_f32 v0, v206, v209
	v_cvt_pk_bf16_f32 v1, v211, v213
	v_cvt_pk_bf16_f32 v2, v217, v218
	v_cvt_pk_bf16_f32 v3, v219, v90
	v_lshl_add_u64 v[4:5], v[112:113], 0, s[20:21]
	global_store_dwordx4 v[4:5], v[0:3], off sc1
	s_nop 1
	v_cvt_pk_bf16_f32 v0, v91, v118
	v_cvt_pk_bf16_f32 v1, v117, v116
	v_cvt_pk_bf16_f32 v2, v115, v114
	v_cvt_pk_bf16_f32 v3, v105, v104
	v_lshl_add_u64 v[4:5], v[112:113], 0, s[14:15]
	global_store_dwordx4 v[4:5], v[0:3], off sc1
	s_nop 1
	v_cvt_pk_bf16_f32 v0, v23, v22
	v_cvt_pk_bf16_f32 v1, v21, v20
	v_cvt_pk_bf16_f32 v2, v19, v18
	v_cvt_pk_bf16_f32 v3, v8, v9
	v_lshl_add_u64 v[4:5], v[112:113], 0, s[8:9]
	global_store_dwordx4 v[4:5], v[0:3], off sc1
	s_nop 1
	v_lshl_add_u64 v[0:1], v[112:113], 0, s[16:17]
	v_mov_b32_e32 v89, v110
	global_store_dwordx4 v[0:1], v[88:91], off sc1
	s_nop 1
	s_addc_u32 s31, s31, 0
	s_mov_b64 s[34:35], 0x1c00
	s_waitcnt vmcnt(7)
	v_lshl_add_u64 v[112:113], v[112:113], 0, s[34:35]
	s_cmpk_lg_i32 s30, 0x2000
	v_mov_b32_e32 v4, v201
	v_mov_b32_e32 v96, v198
	v_mov_b32_e32 v16, v200
	v_mov_b32_e32 v104, v197
	v_mov_b32_e32 v6, v199
	v_mov_b32_e32 v148, v202
	s_cbranch_scc0 .LBB0_393
.LBB0_426:
	s_mov_b32 s34, s39
.LBB0_428:
	v_mov_b32_e32 v105, v104
	v_mov_b32_e32 v106, v104
	v_mov_b32_e32 v107, v104
	v_mov_b32_e32 v97, v96
	v_mov_b32_e32 v98, v96
	s_waitcnt lgkmcnt(7)
	v_mfma_f32_16x16x32_bf16 v[114:117], v[24:27], v[56:59], v[104:107]
	v_mov_b32_e32 v99, v96
	v_add_u32_e32 v18, s34, v186
	v_lshl_add_u32 v5, v18, 1, v189
	v_mfma_f32_16x16x32_bf16 v[118:121], v[24:27], v[60:63], v[96:99]
	s_waitcnt lgkmcnt(6)
	v_mfma_f32_16x16x32_bf16 v[128:131], v[28:31], v[64:67], v[114:117]
	s_waitcnt lgkmcnt(5)
	v_mfma_f32_16x16x32_bf16 v[114:117], v[32:35], v[56:59], v[104:107]
	v_mfma_f32_16x16x32_bf16 v[204:207], v[28:31], v[68:71], v[118:121]
	s_waitcnt lgkmcnt(4)
	v_mfma_f32_16x16x32_bf16 v[218:221], v[36:39], v[64:67], v[114:117]
	ds_read_u16 v7, v5
	ds_read_u16 v17, v5 offset:1040
	ds_read_u16 v19, v5 offset:2080
	s_nop 1
	ds_read_u16 v114, v5 offset:3120
	ds_read_u16 v115, v5 offset:4160
	ds_read_u16 v125, v5 offset:5200
	ds_read_u16 v154, v5 offset:6240
	ds_read_u16 v155, v5 offset:7280
	s_waitcnt lgkmcnt(4)
	v_lshlrev_b32_e32 v123, 16, v114
	s_waitcnt lgkmcnt(3)
	v_lshlrev_b32_e32 v124, 16, v115
	v_mfma_f32_16x16x32_bf16 v[118:121], v[32:35], v[60:63], v[96:99]
	v_lshlrev_b32_e32 v126, 16, v7
	v_lshlrev_b32_e32 v127, 16, v17
	v_lshlrev_b32_e32 v122, 16, v19
	v_mfma_f32_16x16x32_bf16 v[114:117], v[40:43], v[56:59], v[104:107]
	s_waitcnt lgkmcnt(2)
	v_lshlrev_b32_e32 v125, 16, v125
	v_mfma_f32_16x16x32_bf16 v[226:229], v[40:43], v[60:63], v[96:99]
	v_mfma_f32_16x16x32_bf16 v[106:109], v[48:51], v[56:59], v[104:107]
	v_exp_f32_e32 v110, v128
	v_exp_f32_e32 v111, v129
	v_mfma_f32_16x16x32_bf16 v[96:99], v[48:51], v[60:63], v[96:99]
	v_exp_f32_e32 v102, v204
	v_exp_f32_e32 v103, v205
	v_pk_add_f32 v[100:101], v[110:111], 1.0 op_sel_hi:[1,0]
	v_mfma_f32_16x16x32_bf16 v[222:225], v[36:39], v[68:71], v[118:121]
	v_rcp_f32_e32 v100, v100
	v_rcp_f32_e32 v101, v101
	v_mfma_f32_16x16x32_bf16 v[226:229], v[44:47], v[68:71], v[226:229]
	s_waitcnt lgkmcnt(1)
	v_lshlrev_b32_e32 v120, 16, v154
	s_waitcnt lgkmcnt(0)
	v_lshlrev_b32_e32 v121, 16, v155
	ds_read_u16 v7, v5 offset:8320
	ds_read_u16 v17, v5 offset:9360
	ds_read_u16 v19, v5 offset:10400
	ds_read_u16 v154, v5 offset:11440
	ds_read_u16 v155, v5 offset:12480
	ds_read_u16 v203, v5 offset:13520
	ds_read_u16 v208, v5 offset:14560
	ds_read_u16 v5, v5 offset:15600
	v_mfma_f32_16x16x32_bf16 v[88:91], v[52:55], v[68:71], v[96:99]
	v_exp_f32_e32 v209, v229
	s_waitcnt lgkmcnt(7)
	v_lshlrev_b32_e32 v118, 16, v7
	s_waitcnt lgkmcnt(1)
	v_lshlrev_b32_e32 v104, 16, v208
	v_pk_add_f32 v[98:99], v[102:103], 1.0 op_sel_hi:[1,0]
	v_exp_f32_e32 v102, v130
	v_exp_f32_e32 v103, v131
	v_pk_mul_f32 v[96:97], v[100:101], v[6:7] op_sel_hi:[1,0]
	v_mfma_f32_16x16x32_bf16 v[230:233], v[44:47], v[64:67], v[114:117]
	v_exp_f32_e32 v96, v96
	v_pk_add_f32 v[102:103], v[102:103], 1.0 op_sel_hi:[1,0]
	v_exp_f32_e32 v97, v97
	v_rcp_f32_e32 v102, v102
	v_rcp_f32_e32 v103, v103
	s_waitcnt lgkmcnt(0)
	v_lshlrev_b32_e32 v105, 16, v5
	v_pk_fma_f32 v[100:101], v[96:97], v[96:97], 1.0 op_sel_hi:[1,1,0] neg_lo:[1,0,0] neg_hi:[1,0,0] clamp
	v_mfma_f32_16x16x32_bf16 v[92:95], v[52:55], v[64:67], v[106:109]
	v_mul_f32_e64 v102, v102, v6
	v_mul_f32_e64 v103, v103, v6
	v_exp_f32_e32 v110, v102
	v_exp_f32_e32 v111, v103
	v_exp_f32_e32 v102, v218
	s_cmpk_eq_i32 s30, 0x1800
	s_cbranch_scc1 .Lsl_skip1
	v_lshl_add_u64 v[64:65], v[242:243], 0, s[30:31]
	v_lshl_add_u64 v[68:69], v[244:245], 0, s[30:31]
	v_add_u32_e32 v197, s39, v193
	v_add_u32_e32 v199, s39, v194
	global_load_dwordx4 v[56:59], v[64:65], off offset:2048
	global_load_dwordx4 v[60:63], v[68:69], off offset:2048
	v_lshlrev_b32_e32 v197, 2, v197
	v_lshlrev_b32_e32 v199, 2, v199
	global_load_dwordx4 v[64:67], v[64:65], off offset:2112
	s_nop 0
	global_load_dwordx4 v[68:71], v[68:69], off offset:2112
	global_load_dword v198, v197, s[22:23] offset:2112
	s_nop 0
	global_load_dword v197, v197, s[22:23] offset:64
	global_load_dword v199, v199, s[6:7] offset:64
.Lsl_skip1:
	v_exp_f32_e32 v103, v219
	v_exp_f32_e32 v108, v222
	v_exp_f32_e32 v109, v223
	v_rcp_f32_e32 v98, v98
	v_rcp_f32_e32 v99, v99
	v_sqrt_f32_e32 v100, v100
	v_sqrt_f32_e32 v101, v101
	v_exp_f32_e32 v106, v206
	v_exp_f32_e32 v107, v207
	v_pk_add_f32 v[102:103], v[102:103], 1.0 op_sel_hi:[1,0]
	v_pk_add_f32 v[108:109], v[108:109], 1.0 op_sel_hi:[1,0]
	v_rcp_f32_e32 v102, v102
	v_rcp_f32_e32 v103, v103
	v_pk_mul_f32 v[98:99], v[98:99], v[126:127]
	v_rcp_f32_e32 v108, v108
	v_rcp_f32_e32 v109, v109
	v_pk_mul_f32 v[98:99], v[98:99], v[100:101]
	v_pk_add_f32 v[100:101], v[106:107], 1.0 op_sel_hi:[1,0]
	v_pk_fma_f32 v[106:107], v[110:111], v[110:111], 1.0 op_sel_hi:[1,1,0] neg_lo:[1,0,0] neg_hi:[1,0,0] clamp
	v_rcp_f32_e32 v100, v100
	v_rcp_f32_e32 v101, v101
	v_sqrt_f32_e32 v106, v106
	v_pk_mul_f32 v[102:103], v[102:103], v[6:7] op_sel_hi:[1,0]
	v_sqrt_f32_e32 v107, v107
	v_exp_f32_e32 v128, v102
	v_exp_f32_e32 v129, v103
	v_pk_mul_f32 v[102:103], v[108:109], v[124:125]
	v_exp_f32_e32 v108, v220
	v_exp_f32_e32 v109, v221
	v_pk_mul_f32 v[100:101], v[100:101], v[122:123]
	v_exp_f32_e32 v204, v230
	v_pk_mul_f32 v[100:101], v[100:101], v[106:107]
	v_pk_fma_f32 v[106:107], v[128:129], v[128:129], 1.0 op_sel_hi:[1,1,0] neg_lo:[1,0,0] neg_hi:[1,0,0] clamp
	v_pk_add_f32 v[108:109], v[108:109], 1.0 op_sel_hi:[1,0]
	v_exp_f32_e32 v205, v231
	v_rcp_f32_e32 v108, v108
	v_rcp_f32_e32 v109, v109
	v_sqrt_f32_e32 v106, v106
	v_sqrt_f32_e32 v107, v107
	v_pk_add_f32 v[204:205], v[204:205], 1.0 op_sel_hi:[1,0]
	v_pk_mul_f32 v[108:109], v[108:109], v[6:7] op_sel_hi:[1,0]
	v_rcp_f32_e32 v204, v204
	v_rcp_f32_e32 v205, v205
	v_exp_f32_e32 v130, v108
	v_exp_f32_e32 v131, v109
	v_pk_mul_f32 v[102:103], v[102:103], v[106:107]
	v_exp_f32_e32 v106, v224
	v_exp_f32_e32 v107, v225
	v_pk_mul_f32 v[204:205], v[6:7], v[204:205] op_sel_hi:[0,1]
	v_pk_fma_f32 v[108:109], v[130:131], v[130:131], 1.0 op_sel_hi:[1,1,0] neg_lo:[1,0,0] neg_hi:[1,0,0] clamp
	v_exp_f32_e32 v218, v204
	v_exp_f32_e32 v219, v205
	v_exp_f32_e32 v204, v232
	v_exp_f32_e32 v205, v233
	v_pk_add_f32 v[106:107], v[106:107], 1.0 op_sel_hi:[1,0]
	v_rcp_f32_e32 v106, v106
	v_rcp_f32_e32 v107, v107
	v_sqrt_f32_e32 v108, v108
	v_sqrt_f32_e32 v109, v109
	v_exp_f32_e32 v206, v226
	v_exp_f32_e32 v207, v227
	v_pk_add_f32 v[204:205], v[204:205], 1.0 op_sel_hi:[1,0]
	v_pk_mul_f32 v[106:107], v[106:107], v[120:121]
	v_rcp_f32_e32 v204, v204
	v_rcp_f32_e32 v205, v205
	v_pk_mul_f32 v[106:107], v[106:107], v[108:109]
	v_pk_add_f32 v[108:109], v[206:207], 1.0 op_sel_hi:[1,0]
	v_pk_fma_f32 v[206:207], v[218:219], v[218:219], 1.0 op_sel_hi:[1,1,0] neg_lo:[1,0,0] neg_hi:[1,0,0] clamp
	v_exp_f32_e32 v208, v228
	v_rcp_f32_e32 v108, v108
	v_rcp_f32_e32 v109, v109
	v_sqrt_f32_e32 v206, v206
	v_pk_mul_f32 v[204:205], v[6:7], v[204:205] op_sel_hi:[0,1]
	v_sqrt_f32_e32 v207, v207
	v_exp_f32_e32 v220, v204
	v_exp_f32_e32 v221, v205
	v_lshlrev_b32_e32 v119, 16, v17
	v_pk_add_f32 v[208:209], v[208:209], 1.0 op_sel_hi:[1,0]
	v_exp_f32_e32 v92, v92
	v_exp_f32_e32 v93, v93
	v_rcp_f32_e32 v208, v208
	v_rcp_f32_e32 v209, v209
	v_pk_mul_f32 v[108:109], v[108:109], v[118:119]
	v_exp_f32_e32 v94, v94
	v_pk_mul_f32 v[108:109], v[108:109], v[206:207]
	v_pk_fma_f32 v[206:207], v[220:221], v[220:221], 1.0 op_sel_hi:[1,1,0] neg_lo:[1,0,0] neg_hi:[1,0,0] clamp
	v_exp_f32_e32 v95, v95
	v_lshlrev_b32_e32 v116, 16, v19
	v_lshlrev_b32_e32 v117, 16, v154
	v_sqrt_f32_e32 v206, v206
	v_pk_add_f32 v[92:93], v[92:93], 1.0 op_sel_hi:[1,0]
	v_pk_mul_f32 v[204:205], v[208:209], v[116:117]
	v_sqrt_f32_e32 v207, v207
	v_rcp_f32_e32 v208, v92
	v_rcp_f32_e32 v209, v93
	v_pk_add_f32 v[94:95], v[94:95], 1.0 op_sel_hi:[1,0]
	v_pk_mul_f32 v[92:93], v[204:205], v[206:207]
	v_rcp_f32_e32 v94, v94
	v_rcp_f32_e32 v95, v95
	v_pk_mul_f32 v[204:205], v[6:7], v[208:209] op_sel_hi:[0,1]
	v_exp_f32_e32 v222, v204
	v_exp_f32_e32 v223, v205
	v_exp_f32_e32 v88, v88
	v_exp_f32_e32 v89, v89
	v_pk_mul_f32 v[6:7], v[6:7], v[94:95] op_sel_hi:[0,1]
	v_exp_f32_e32 v6, v6
	v_exp_f32_e32 v7, v7
	v_exp_f32_e32 v90, v90
	v_exp_f32_e32 v91, v91
	v_pk_fma_f32 v[204:205], v[222:223], v[222:223], 1.0 op_sel_hi:[1,1,0] neg_lo:[1,0,0] neg_hi:[1,0,0] clamp
	v_pk_add_f32 v[88:89], v[88:89], 1.0 op_sel_hi:[1,0]
	v_rcp_f32_e32 v88, v88
	v_rcp_f32_e32 v89, v89
	v_sqrt_f32_e32 v204, v204
	v_pk_fma_f32 v[94:95], v[6:7], v[6:7], 1.0 op_sel_hi:[1,1,0] neg_lo:[1,0,0] neg_hi:[1,0,0] clamp
	v_sqrt_f32_e32 v205, v205
	v_pk_add_f32 v[90:91], v[90:91], 1.0 op_sel_hi:[1,0]
	v_rcp_f32_e32 v90, v90
	v_rcp_f32_e32 v91, v91
	v_sqrt_f32_e32 v206, v94
	v_fma_f32 v98, 0, v96, v98
	v_lshlrev_b32_e32 v114, 16, v155
	v_lshlrev_b32_e32 v115, 16, v203
	v_sqrt_f32_e32 v207, v95
	v_fmac_f32_e32 v99, v97, v98
	v_mul_f32_e32 v97, v96, v97
	v_pk_mul_f32 v[88:89], v[88:89], v[114:115]
	v_mul_f32_e32 v203, v110, v97
	v_fma_f32 v100, v110, v99, v100
	v_pk_mul_f32 v[94:95], v[88:89], v[204:205]
	v_fmac_f32_e32 v101, v111, v100
	v_mul_f32_e32 v204, v111, v203
	v_pk_mul_f32 v[88:89], v[90:91], v[104:105]
	v_mul_f32_e32 v205, v128, v204
	v_fma_f32 v102, v128, v101, v102
	v_pk_mul_f32 v[88:89], v[88:89], v[206:207]
	v_fmac_f32_e32 v103, v129, v102
	v_mul_f32_e32 v207, v129, v205
	v_mul_f32_e32 v208, v130, v207
	v_fma_f32 v106, v130, v103, v106
	v_fmac_f32_e32 v107, v131, v106
	v_mul_f32_e32 v212, v131, v208
	v_mul_f32_e32 v206, v218, v212
	v_fma_f32 v108, v218, v107, v108
	v_fmac_f32_e32 v109, v219, v108
	v_mul_f32_e32 v209, v219, v206
	v_mul_f32_e32 v211, v220, v209
	v_fma_f32 v92, v220, v109, v92
	v_fmac_f32_e32 v93, v221, v92
	v_mul_f32_e32 v213, v221, v211
	v_mul_f32_e32 v217, v222, v213
	v_fma_f32 v94, v222, v93, v94
	v_fmac_f32_e32 v95, v223, v94
	v_mul_f32_e32 v218, v223, v217
	v_mul_f32_e32 v219, v6, v218
	v_fma_f32 v88, v6, v95, v88
	v_fmac_f32_e32 v89, v7, v88
	v_mul_f32_e32 v90, v7, v219
	ds_bpermute_b32 v110, v182, v90
	ds_bpermute_b32 v5, v182, v89
	ds_bpermute_b32 v111, v190, v90
	ds_bpermute_b32 v17, v190, v89
	ds_bpermute_b32 v130, v191, v90
	ds_bpermute_b32 v91, v191, v89
	ds_bpermute_b32 v131, v192, v90
	ds_bpermute_b32 v7, v192, v89
	v_ashrrev_i32_e32 v19, 31, v18
	v_lshl_add_u64 v[128:129], v[18:19], 3, s[28:29]
	s_and_saveexec_b64 s[34:35], s[40:41]
	s_cbranch_execz .LBB0_430
	s_waitcnt lgkmcnt(6)
	v_fmac_f32_e32 v5, 0, v110
	s_waitcnt lgkmcnt(5)
	v_mul_f32_e32 v6, v110, v111
	s_waitcnt lgkmcnt(4)
	v_fmac_f32_e32 v17, v5, v111
	s_waitcnt lgkmcnt(3)
	v_mul_f32_e32 v6, v6, v130
	s_waitcnt lgkmcnt(2)
	v_fmac_f32_e32 v91, v17, v130
	s_waitcnt lgkmcnt(1)
	v_mul_f32_e32 v6, v6, v131
	s_waitcnt lgkmcnt(0)
	v_fmac_f32_e32 v7, v91, v131
	global_store_dwordx2 v[128:129], v[6:7], off sc1
.LBB0_430:
	s_or_b64 exec, exec, s[34:35]
	s_waitcnt lgkmcnt(4)
	v_mov_b32_e32 v17, v16
	v_mov_b32_e32 v18, v16
	v_mov_b32_e32 v19, v16
	v_mov_b32_e32 v5, v4
	v_mov_b32_e32 v6, v4
	v_mfma_f32_16x16x32_bf16 v[220:223], v[24:27], v[72:75], v[16:19]
	s_waitcnt lgkmcnt(0)
	v_mov_b32_e32 v7, v4
	v_mfma_f32_16x16x32_bf16 v[220:223], v[28:31], v[76:79], v[220:223]
	s_nop 0
	v_mfma_f32_16x16x32_bf16 v[224:227], v[24:27], v[80:83], v[4:7]
	v_mfma_f32_16x16x32_bf16 v[224:227], v[28:31], v[84:87], v[224:227]
	s_nop 4
	v_exp_f32_e32 v110, v220
	v_exp_f32_e32 v111, v221
	v_mfma_f32_16x16x32_bf16 v[228:231], v[32:35], v[72:75], v[16:19]
	v_add_f32_e64 v110, v110, 1.0
	v_add_f32_e64 v111, v111, 1.0
	v_exp_f32_e32 v130, v224
	v_exp_f32_e32 v131, v225
	v_rcp_f32_e32 v110, v110
	v_rcp_f32_e32 v111, v111
	v_mfma_f32_16x16x32_bf16 v[228:231], v[36:39], v[76:79], v[228:231]
	v_add_f32_e64 v130, v130, 1.0
	v_add_f32_e64 v131, v131, 1.0
	v_exp_f32_e32 v224, v222
	v_pk_mul_f32 v[110:111], v[110:111], v[148:149] op_sel_hi:[1,0]
	v_rcp_f32_e32 v220, v130
	v_rcp_f32_e32 v221, v131
	v_exp_f32_e32 v130, v110
	v_exp_f32_e32 v131, v111
	v_exp_f32_e32 v225, v223
	v_pk_mul_f32 v[110:111], v[220:221], v[126:127]
	v_mfma_f32_16x16x32_bf16 v[220:223], v[40:43], v[72:75], v[16:19]
	v_fma_f32 v126, -v130, v130, 1.0
	v_fma_f32 v127, -v131, v131, 1.0
	v_pk_add_f32 v[224:225], v[224:225], 1.0 op_sel_hi:[1,0]
	v_max_f32_e32 v91, 0, v126
	v_sqrt_f32_e32 v126, v91
	v_max_f32_e32 v91, 0, v127
	v_mfma_f32_16x16x32_bf16 v[16:19], v[48:51], v[72:75], v[16:19]
	v_exp_f32_e32 v22, v228
	v_exp_f32_e32 v23, v229
	v_sqrt_f32_e32 v127, v91
	v_mfma_f32_16x16x32_bf16 v[232:235], v[32:35], v[80:83], v[4:7]
	v_exp_f32_e32 v226, v226
	v_exp_f32_e32 v227, v227
	v_rcp_f32_e32 v224, v224
	v_mfma_f32_16x16x32_bf16 v[236:239], v[40:43], v[80:83], v[4:7]
	v_rcp_f32_e32 v225, v225
	v_pk_mul_f32 v[110:111], v[110:111], v[126:127]
	v_pk_add_f32 v[240:241], v[226:227], 1.0 op_sel_hi:[1,0]
	v_mfma_f32_16x16x32_bf16 v[4:7], v[48:51], v[80:83], v[4:7]
	v_mul_f32_e64 v126, v224, v148
	v_mul_f32_e64 v127, v225, v148
	v_exp_f32_e32 v126, v126
	v_mfma_f32_16x16x32_bf16 v[220:223], v[44:47], v[76:79], v[220:223]
	v_exp_f32_e32 v127, v127
	s_nop 0
	v_pk_fma_f32 v[20:21], v[126:127], v[126:127], 1.0 op_sel_hi:[1,1,0] neg_lo:[1,0,0] neg_hi:[1,0,0] clamp
	v_mfma_f32_16x16x32_bf16 v[10:13], v[52:55], v[76:79], v[16:19]
	v_sqrt_f32_e32 v8, v20
	s_nop 0
	v_pk_add_f32 v[18:19], v[22:23], 1.0 op_sel_hi:[1,0]
	v_mfma_f32_16x16x32_bf16 v[232:235], v[36:39], v[84:87], v[232:235]
	s_nop 2
	v_exp_f32_e32 v10, v10
	v_exp_f32_e32 v11, v11
	v_exp_f32_e32 v12, v12
	v_mfma_f32_16x16x32_bf16 v[224:227], v[44:47], v[84:87], v[236:239]
	v_exp_f32_e32 v13, v13
	v_exp_f32_e32 v22, v232
	v_exp_f32_e32 v23, v233
	v_mfma_f32_16x16x32_bf16 v[14:17], v[52:55], v[84:87], v[4:7]
	v_rcp_f32_e32 v0, v18
	v_rcp_f32_e32 v1, v19
	v_rcp_f32_e32 v236, v240
	v_rcp_f32_e32 v237, v241
	s_cmpk_eq_i32 s30, 0x1800
	s_cbranch_scc1 .Lsl_skip2
	v_lshl_add_u64 v[76:77], v[246:247], 0, s[30:31]
	v_lshl_add_u64 v[84:85], v[248:249], 0, s[30:31]
	v_add_u32_e32 v200, s39, v193
	v_add_u32_e32 v202, s39, v194
	global_load_dwordx4 v[72:75], v[76:77], off offset:2048
	global_load_dwordx4 v[80:83], v[84:85], off offset:2048
	v_lshlrev_b32_e32 v200, 2, v200
	v_lshlrev_b32_e32 v202, 2, v202
	global_load_dwordx4 v[76:79], v[76:77], off offset:2112
	v_add_u32_e32 v200, 0x1000, v200
	global_load_dwordx4 v[84:87], v[84:85], off offset:2112
	global_load_dword v201, v200, s[22:23] offset:2112
	s_nop 0
	global_load_dword v200, v200, s[22:23] offset:64
	global_load_dword v202, v202, s[6:7] offset:2112
.Lsl_skip2:
	v_pk_mul_f32 v[0:1], v[0:1], v[148:149] op_sel_hi:[1,0]
	v_sqrt_f32_e32 v9, v21
	v_exp_f32_e32 v228, v0
	v_exp_f32_e32 v229, v1
	v_pk_add_f32 v[2:3], v[22:23], 1.0 op_sel_hi:[1,0]
	v_exp_f32_e32 v6, v230
	v_rcp_f32_e32 v2, v2
	v_pk_fma_f32 v[4:5], v[228:229], v[228:229], 1.0 op_sel_hi:[1,1,0] neg_lo:[1,0,0] neg_hi:[1,0,0] clamp
	v_rcp_f32_e32 v3, v3
	v_sqrt_f32_e32 v4, v4
	v_sqrt_f32_e32 v5, v5
	v_exp_f32_e32 v7, v231
	v_pk_mul_f32 v[0:1], v[236:237], v[122:123]
	v_pk_mul_f32 v[2:3], v[2:3], v[124:125]
	v_pk_mul_f32 v[0:1], v[0:1], v[8:9]
	v_exp_f32_e32 v8, v220
	v_exp_f32_e32 v9, v221
	v_pk_mul_f32 v[2:3], v[2:3], v[4:5]
	v_exp_f32_e32 v4, v234
	v_exp_f32_e32 v5, v235
	v_pk_add_f32 v[6:7], v[6:7], 1.0 op_sel_hi:[1,0]
	v_pk_add_f32 v[8:9], v[8:9], 1.0 op_sel_hi:[1,0]
	v_rcp_f32_e32 v6, v6
	v_rcp_f32_e32 v7, v7
	v_pk_add_f32 v[4:5], v[4:5], 1.0 op_sel_hi:[1,0]
	v_rcp_f32_e32 v8, v8
	v_rcp_f32_e32 v9, v9
	v_rcp_f32_e32 v4, v4
	v_rcp_f32_e32 v5, v5
	v_pk_mul_f32 v[6:7], v[6:7], v[148:149] op_sel_hi:[1,0]
	v_pk_mul_f32 v[8:9], v[148:149], v[8:9] op_sel_hi:[0,1]
	v_exp_f32_e32 v122, v6
	v_exp_f32_e32 v123, v7
	v_pk_mul_f32 v[4:5], v[4:5], v[120:121]
	v_exp_f32_e32 v120, v8
	v_exp_f32_e32 v121, v9
	v_exp_f32_e32 v8, v222
	v_exp_f32_e32 v9, v223
	v_pk_fma_f32 v[6:7], v[122:123], v[122:123], 1.0 op_sel_hi:[1,1,0] neg_lo:[1,0,0] neg_hi:[1,0,0] clamp
	v_exp_f32_e32 v18, v224
	v_sqrt_f32_e32 v6, v6
	v_sqrt_f32_e32 v7, v7
	v_exp_f32_e32 v19, v225
	v_pk_add_f32 v[8:9], v[8:9], 1.0 op_sel_hi:[1,0]
	v_exp_f32_e32 v20, v226
	v_rcp_f32_e32 v8, v8
	v_rcp_f32_e32 v9, v9
	v_exp_f32_e32 v21, v227
	v_pk_mul_f32 v[4:5], v[4:5], v[6:7]
	v_pk_add_f32 v[6:7], v[18:19], 1.0 op_sel_hi:[1,0]
	v_pk_fma_f32 v[18:19], v[120:121], v[120:121], 1.0 op_sel_hi:[1,1,0] neg_lo:[1,0,0] neg_hi:[1,0,0] clamp
	v_rcp_f32_e32 v6, v6
	v_rcp_f32_e32 v7, v7
	v_pk_mul_f32 v[8:9], v[148:149], v[8:9] op_sel_hi:[0,1]
	v_sqrt_f32_e32 v18, v18
	v_sqrt_f32_e32 v19, v19
	v_exp_f32_e32 v22, v8
	v_exp_f32_e32 v23, v9
	v_pk_add_f32 v[20:21], v[20:21], 1.0 op_sel_hi:[1,0]
	v_pk_mul_f32 v[6:7], v[6:7], v[118:119]
	v_rcp_f32_e32 v20, v20
	v_rcp_f32_e32 v21, v21
	v_pk_mul_f32 v[6:7], v[6:7], v[18:19]
	v_pk_fma_f32 v[18:19], v[22:23], v[22:23], 1.0 op_sel_hi:[1,1,0] neg_lo:[1,0,0] neg_hi:[1,0,0] clamp
	v_pk_add_f32 v[10:11], v[10:11], 1.0 op_sel_hi:[1,0]
	v_pk_mul_f32 v[8:9], v[20:21], v[116:117]
	v_sqrt_f32_e32 v18, v18
	v_sqrt_f32_e32 v19, v19
	v_rcp_f32_e32 v20, v10
	v_rcp_f32_e32 v21, v11
	v_pk_mul_f32 v[10:11], v[8:9], v[18:19]
	v_exp_f32_e32 v8, v14
	v_exp_f32_e32 v9, v15
	v_pk_mul_f32 v[14:15], v[148:149], v[20:21] op_sel_hi:[0,1]
	v_exp_f32_e32 v20, v14
	v_exp_f32_e32 v21, v15
	v_pk_add_f32 v[8:9], v[8:9], 1.0 op_sel_hi:[1,0]
	s_nop 0
	v_rcp_f32_e32 v14, v8
	v_rcp_f32_e32 v15, v9
	v_pk_fma_f32 v[8:9], v[20:21], v[20:21], 1.0 op_sel_hi:[1,1,0] neg_lo:[1,0,0] neg_hi:[1,0,0] clamp
	v_pk_mul_f32 v[14:15], v[14:15], v[114:115]
	v_sqrt_f32_e32 v18, v8
	v_max_f32_e32 v19, 0, v9
	v_pk_add_f32 v[8:9], v[12:13], 1.0 op_sel_hi:[1,0]
	v_exp_f32_e32 v12, v16
	v_rcp_f32_e32 v8, v8
	v_rcp_f32_e32 v9, v9
	v_exp_f32_e32 v13, v17
	v_sqrt_f32_e32 v19, v19
	v_pk_mul_f32 v[8:9], v[148:149], v[8:9] op_sel_hi:[0,1]
	v_exp_f32_e32 v8, v8
	v_exp_f32_e32 v9, v9
	v_pk_add_f32 v[12:13], v[12:13], 1.0 op_sel_hi:[1,0]
	v_pk_mul_f32 v[14:15], v[14:15], v[18:19]
	v_rcp_f32_e32 v12, v12
	v_pk_fma_f32 v[16:17], v[8:9], v[8:9], 1.0 op_sel_hi:[1,1,0] neg_lo:[1,0,0] neg_hi:[1,0,0] clamp
	v_rcp_f32_e32 v13, v13
	v_sqrt_f32_e32 v16, v16
	v_sqrt_f32_e32 v17, v17
	v_pk_mul_f32 v[12:13], v[12:13], v[104:105]
	s_nop 0
	v_pk_mul_f32 v[12:13], v[12:13], v[16:17]
	s_nop 0
	v_fma_f32 v13, 0, v9, v13
	v_fmac_f32_e32 v12, v8, v13
	v_mul_f32_e32 v8, v9, v8
	v_mul_f32_e32 v18, v21, v8
	v_fma_f32 v15, v21, v12, v15
	v_fmac_f32_e32 v14, v20, v15
	v_mul_f32_e32 v19, v20, v18
	v_mul_f32_e32 v20, v23, v19
	v_fma_f32 v11, v23, v14, v11
	v_fmac_f32_e32 v10, v22, v11
	v_mul_f32_e32 v21, v22, v20
	v_mul_f32_e32 v22, v121, v21
	v_fma_f32 v7, v121, v10, v7
	v_fmac_f32_e32 v6, v120, v7
	v_mul_f32_e32 v23, v120, v22
	v_mul_f32_e32 v104, v123, v23
	v_fma_f32 v5, v123, v6, v5
	v_fmac_f32_e32 v4, v122, v5
	v_mul_f32_e32 v105, v122, v104
	v_mul_f32_e32 v114, v229, v105
	v_fma_f32 v3, v229, v4, v3
	v_fmac_f32_e32 v2, v228, v3
	v_mul_f32_e32 v115, v228, v114
	v_mul_f32_e32 v116, v127, v115
	v_fma_f32 v1, v127, v2, v1
	v_fmac_f32_e32 v0, v126, v1
	v_mul_f32_e32 v117, v126, v116
	v_mul_f32_e32 v118, v131, v117
	v_fma_f32 v111, v131, v0, v111
	v_fmac_f32_e32 v110, v130, v111
	v_mul_f32_e32 v91, v130, v118
	ds_bpermute_b32 v122, v192, v91
	ds_bpermute_b32 v119, v192, v110
	ds_bpermute_b32 v123, v191, v91
	ds_bpermute_b32 v120, v191, v110
	ds_bpermute_b32 v124, v190, v91
	ds_bpermute_b32 v121, v190, v110
	ds_bpermute_b32 v125, v182, v91
	ds_bpermute_b32 v17, v182, v110
	s_and_saveexec_b64 s[34:35], s[40:41]
	s_cbranch_execz .LBB0_425
	s_waitcnt lgkmcnt(6)
	v_fmac_f32_e32 v119, 0, v122
	s_waitcnt lgkmcnt(5)
	v_mul_f32_e32 v16, v122, v123
	s_waitcnt lgkmcnt(4)
	v_fmac_f32_e32 v120, v119, v123
	s_waitcnt lgkmcnt(3)
	v_mul_f32_e32 v16, v16, v124
	s_waitcnt lgkmcnt(2)
	v_fmac_f32_e32 v121, v120, v124
	v_add_co_u32_e32 v120, vcc, 0x1000, v128
	s_waitcnt lgkmcnt(1)
	v_mul_f32_e32 v16, v16, v125
	s_waitcnt lgkmcnt(0)
	v_fmac_f32_e32 v17, v121, v125
	v_addc_co_u32_e32 v121, vcc, 0, v129, vcc
	global_store_dwordx2 v[120:121], v[16:17], off sc1
	s_branch .LBB0_425

.LBB0_506:
	s_or_b64 exec, exec, s[34:35]
	s_waitcnt lgkmcnt(4)
	s_waitcnt lgkmcnt(0)
	v_pk_add_f32 v[26:27], v[76:77], v[32:33]
	s_mul_i32 s96, s48, 0x1c00
	v_pk_add_f32 v[20:21], v[80:81], v[20:21]
	v_pk_add_f32 v[10:11], v[74:75], v[24:25]
	v_pk_add_f32 v[22:23], v[84:85], v[22:23]
	v_lshl_add_u64 v[40:41], v[70:71], 0, s[96:97]
	v_pk_add_f32 v[12:13], v[86:87], v[12:13]
	s_xor_b64 s[34:35], s[28:29], -1
	v_pk_add_f32 v[14:15], v[88:89], v[14:15]
	s_mov_b32 s48, 1
	v_pk_add_f32 v[4:5], v[60:61], v[4:5]
	v_pk_add_f32 v[32:33], v[0:1], v[8:9]
	v_mov_b32_e32 v0, v1
	v_cvt_pk_bf16_f32 v8, v10, v11
	v_cvt_pk_bf16_f32 v9, v26, v27
	v_cvt_pk_bf16_f32 v10, v20, v21
	v_cvt_pk_bf16_f32 v11, v22, v23
	global_store_dwordx4 v[40:41], v[8:11], off sc1
	s_nop 1
	v_cvt_pk_bf16_f32 v8, v12, v13
	v_cvt_pk_bf16_f32 v9, v14, v15
	v_cvt_pk_bf16_f32 v10, v4, v5
	v_cvt_pk_bf16_f32 v11, v32, v33
	v_lshl_add_u64 v[4:5], v[40:41], 0, s[18:19]
	global_store_dwordx4 v[4:5], v[8:11], off sc1
	s_nop 1
	v_cvt_pk_bf16_f32 v8, v72, v73
	v_cvt_pk_bf16_f32 v9, v116, v106
	v_cvt_pk_bf16_f32 v10, v107, v118
	v_cvt_pk_bf16_f32 v11, v119, v122
	v_lshl_add_u64 v[4:5], v[40:41], 0, s[12:13]
	global_store_dwordx4 v[4:5], v[8:11], off sc1
	s_nop 1
	v_cvt_pk_bf16_f32 v8, v117, v120
	v_cvt_pk_bf16_f32 v9, v121, v123
	v_cvt_pk_bf16_f32 v10, v124, v125
	v_cvt_pk_bf16_f32 v11, v126, v2
	v_lshl_add_u64 v[4:5], v[40:41], 0, s[20:21]
	global_store_dwordx4 v[4:5], v[8:11], off sc1
	s_nop 1
	v_cvt_pk_bf16_f32 v8, v3, v35
	v_cvt_pk_bf16_f32 v9, v34, v29
	v_cvt_pk_bf16_f32 v10, v28, v31
	v_cvt_pk_bf16_f32 v11, v30, v17
	v_lshl_add_u64 v[4:5], v[40:41], 0, s[14:15]
	global_store_dwordx4 v[4:5], v[8:11], off sc1
	s_nop 1
	v_cvt_pk_bf16_f32 v8, v16, v19
	v_cvt_pk_bf16_f32 v9, v18, v38
	v_cvt_pk_bf16_f32 v10, v37, v36
	v_cvt_pk_bf16_f32 v11, v6, v7
	v_lshl_add_u64 v[4:5], v[40:41], 0, s[8:9]
	global_store_dwordx4 v[4:5], v[8:11], off sc1
	s_nop 1
	v_lshl_add_u64 v[4:5], v[40:41], 0, s[16:17]
	v_mov_b32_e32 v1, v24
	global_store_dwordx4 v[4:5], v[0:3], off sc1
	s_nop 1
	s_mov_b64 s[28:29], 0
	s_and_b64 vcc, exec, s[34:35]
	s_cbranch_vccnz .LBB0_511
